# GEMM K-loops: static priority raise for the leading wave half instead of per-cluster flips
# baseline (speedup 1.0000x reference)
; template <class Epi, class Sched, bool ALIGN_EPI = false, bool SP2 = false>
; __device__ __forceinline__ void gemm_phase(PG8_LAS unsigned char* lds, const Gemm g, const Sched& S, const Epi& E) {
;     ...
;         const bool has_next = S.next(ui + 1, nxt);
;         const char* nA = has_next ? (const char*)g.A + (size_t)nxt.pm * tstep : cA; const char* nB = has_next ? (const char*)g.Bt + (size_t)nxt.pn * tstep : cB;
;     ...
; #pragma unroll
;         for (int a = 0; a < 2; ++a)
; #pragma unroll
;             for (int b = 0; b < 2; ++b)
; #pragma unroll
;                 for (int m = 0; m < 4; ++m)
; #pragma unroll
;                     for (int n = 0; n < 2; ++n) acc[a][b][m][n] = (f32x4){0.f, 0.f, 0.f, 0.f};
;         cur = nxt; cA = nA; cB = nB; ++ui;
.LBB0_386:
	s_ashr_i32 s77, s76, 31
	s_lshl_b64 s[44:45], s[76:77], 19
	s_add_u32 s78, s26, s44
	s_addc_u32 s79, s27, s45
	s_and_b64 s[44:45], s[4:5], exec
	s_cselect_b32 s2, s79, s83
	s_cselect_b32 s7, s78, s82
	s_ashr_i32 s75, s74, 31
	s_lshl_b64 s[44:45], s[74:75], 19
	s_add_u32 s80, s50, s44
	s_addc_u32 s81, s51, s45
	s_and_b64 s[44:45], s[4:5], exec
	s_cselect_b32 s12, s81, s85
	s_cselect_b32 s17, s80, s84
	s_add_u32 s82, s82, 0x40080
	.p2align 6
	s_addc_u32 s83, s83, 0
	s_add_u32 s44, s84, 0x100
	v_mov_b32_e32 v0, 0
	s_addc_u32 s45, s85, 0
	s_mov_b32 s75, -2
	v_mov_b32_e32 v1, v0
	s_waitcnt lgkmcnt(0)
	v_mov_b32_e32 v2, v0
	v_mov_b32_e32 v3, v0
	v_mov_b32_e32 v8, v0
	v_mov_b32_e32 v9, v0
	v_mov_b32_e32 v10, v0
	v_mov_b32_e32 v11, v0
	v_mov_b32_e32 v16, v0
	v_mov_b32_e32 v17, v0
	v_mov_b32_e32 v18, v0
	v_mov_b32_e32 v19, v0
	v_mov_b32_e32 v24, v0
	v_mov_b32_e32 v25, v0
	v_mov_b32_e32 v26, v0
	v_mov_b32_e32 v27, v0
	v_mov_b32_e32 v32, v0
	v_mov_b32_e32 v33, v0
	v_mov_b32_e32 v34, v0
	v_mov_b32_e32 v35, v0
	v_mov_b32_e32 v40, v0
	v_mov_b32_e32 v41, v0
	v_mov_b32_e32 v42, v0
	v_mov_b32_e32 v43, v0
	v_mov_b32_e32 v48, v0
	v_mov_b32_e32 v49, v0
	v_mov_b32_e32 v50, v0
	v_mov_b32_e32 v51, v0
	v_mov_b32_e32 v56, v0
	v_mov_b32_e32 v57, v0
	v_mov_b32_e32 v58, v0
	v_mov_b32_e32 v59, v0
	v_mov_b32_e32 v4, v0
	v_mov_b32_e32 v5, v0
	v_mov_b32_e32 v6, v0
	v_mov_b32_e32 v7, v0
	v_mov_b32_e32 v12, v0
	v_mov_b32_e32 v13, v0
	v_mov_b32_e32 v14, v0
	v_mov_b32_e32 v15, v0
	v_mov_b32_e32 v20, v0
	v_mov_b32_e32 v21, v0
	v_mov_b32_e32 v22, v0
	v_mov_b32_e32 v23, v0
	v_mov_b32_e32 v28, v0
	v_mov_b32_e32 v29, v0
	v_mov_b32_e32 v30, v0
	v_mov_b32_e32 v31, v0
	v_mov_b32_e32 v36, v0
	v_mov_b32_e32 v37, v0
	v_mov_b32_e32 v38, v0
	v_mov_b32_e32 v39, v0
	v_mov_b32_e32 v44, v0
	v_mov_b32_e32 v45, v0
	v_mov_b32_e32 v46, v0
	v_mov_b32_e32 v47, v0
	v_mov_b32_e32 v52, v0
	v_mov_b32_e32 v53, v0
	v_mov_b32_e32 v54, v0
	v_mov_b32_e32 v55, v0
	v_mov_b32_e32 v60, v0
	v_mov_b32_e32 v61, v0
	v_mov_b32_e32 v62, v0
	v_mov_b32_e32 v63, v0
	v_mov_b32_e32 v64, v0
	v_mov_b32_e32 v65, v0
	v_mov_b32_e32 v66, v0
	v_mov_b32_e32 v67, v0
	v_mov_b32_e32 v72, v0
	v_mov_b32_e32 v73, v0
	v_mov_b32_e32 v74, v0
	v_mov_b32_e32 v75, v0
	v_mov_b32_e32 v80, v0
	v_mov_b32_e32 v81, v0
	v_mov_b32_e32 v82, v0
	v_mov_b32_e32 v83, v0
	v_mov_b32_e32 v88, v0
	v_mov_b32_e32 v89, v0
	v_mov_b32_e32 v90, v0
	v_mov_b32_e32 v91, v0
	v_mov_b32_e32 v96, v0
	v_mov_b32_e32 v97, v0
	v_mov_b32_e32 v98, v0
	v_mov_b32_e32 v99, v0
	v_mov_b32_e32 v104, v0
	v_mov_b32_e32 v105, v0
	v_mov_b32_e32 v106, v0
	v_mov_b32_e32 v107, v0
	v_mov_b32_e32 v112, v0
	v_mov_b32_e32 v113, v0
	v_mov_b32_e32 v114, v0
	v_mov_b32_e32 v115, v0
	v_mov_b32_e32 v120, v0
	v_mov_b32_e32 v121, v0
	v_mov_b32_e32 v122, v0
	v_mov_b32_e32 v123, v0
	v_mov_b32_e32 v68, v0
	v_mov_b32_e32 v69, v0
	v_mov_b32_e32 v70, v0
	v_mov_b32_e32 v71, v0
	v_mov_b32_e32 v76, v0
	v_mov_b32_e32 v77, v0
	v_mov_b32_e32 v78, v0
	v_mov_b32_e32 v79, v0
	v_mov_b32_e32 v84, v0
	v_mov_b32_e32 v85, v0
	v_mov_b32_e32 v86, v0
	v_mov_b32_e32 v87, v0
	v_mov_b32_e32 v92, v0
	v_mov_b32_e32 v93, v0
	v_mov_b32_e32 v94, v0
	v_mov_b32_e32 v95, v0
	v_mov_b32_e32 v100, v0
	v_mov_b32_e32 v101, v0
	v_mov_b32_e32 v102, v0
	v_mov_b32_e32 v103, v0
	v_mov_b32_e32 v108, v0
	v_mov_b32_e32 v109, v0
	v_mov_b32_e32 v110, v0
	v_mov_b32_e32 v111, v0
	v_mov_b32_e32 v116, v0
	v_mov_b32_e32 v117, v0
	v_mov_b32_e32 v118, v0
	v_mov_b32_e32 v119, v0
	v_mov_b32_e32 v124, v0
	v_mov_b32_e32 v125, v0
	v_mov_b32_e32 v126, v0
	v_mov_b32_e32 v127, v0
	s_cmp_eq_u64 s[56:57], 0
	s_cbranch_scc1 .Lprio_387
	s_setprio 1

; template <class Epi, class Sched, bool ALIGN_EPI = false, bool SP2 = false>
; __device__ __forceinline__ void gemm_phase(PG8_LAS unsigned char* lds, const Gemm g, const Sched& S, const Epi& E) {
;     ...
;         const bool has_next = S.next(ui + 1, nxt);
;         const char* nA = has_next ? (const char*)g.A + (size_t)nxt.pm * tstep : cA; const char* nB = has_next ? (const char*)g.Bt + (size_t)nxt.pn * tstep : cB;
;     ...
; #pragma unroll
;         for (int a = 0; a < 2; ++a)
; #pragma unroll
;             for (int b = 0; b < 2; ++b)
; #pragma unroll
;                 for (int m = 0; m < 4; ++m)
; #pragma unroll
;                     for (int n = 0; n < 2; ++n) acc[a][b][m][n] = (f32x4){0.f, 0.f, 0.f, 0.f};
;         cur = nxt; cA = nA; cB = nB; ++ui;
.LBB0_749:
	s_ashr_i32 s19, s18, 31
	s_lshl_b64 s[20:21], s[18:19], 19
	s_add_u32 s20, s26, s20
	s_addc_u32 s21, s27, s21
	s_and_b64 s[56:57], s[4:5], exec
	s_cselect_b32 s19, s21, s63
	s_cselect_b32 s56, s20, s62
	s_ashr_i32 s17, s16, 31
	s_lshl_b64 s[58:59], s[16:17], 19
	s_add_u32 s58, s46, s58
	s_addc_u32 s59, s47, s59
	s_and_b64 s[66:67], s[4:5], exec
	s_cselect_b32 s17, s59, s65
	s_cselect_b32 s57, s58, s64
	s_add_u32 s62, s62, 0x40080
	.p2align 6
	s_addc_u32 s63, s63, 0
	s_add_u32 s61, s64, 0x100
	v_mov_b32_e32 v0, 0
	s_addc_u32 s71, s65, 0
	s_mov_b32 s72, -2
	s_waitcnt lgkmcnt(0)
	v_mov_b32_e32 v1, v0
	v_mov_b32_e32 v2, v0
	v_mov_b32_e32 v3, v0
	v_mov_b32_e32 v4, v0
	v_mov_b32_e32 v5, v0
	v_mov_b32_e32 v6, v0
	v_mov_b32_e32 v7, v0
	v_mov_b32_e32 v16, v0
	v_mov_b32_e32 v17, v0
	v_mov_b32_e32 v18, v0
	v_mov_b32_e32 v19, v0
	v_mov_b32_e32 v20, v0
	v_mov_b32_e32 v21, v0
	v_mov_b32_e32 v22, v0
	v_mov_b32_e32 v23, v0
	v_mov_b32_e32 v32, v0
	v_mov_b32_e32 v33, v0
	v_mov_b32_e32 v34, v0
	v_mov_b32_e32 v35, v0
	v_mov_b32_e32 v36, v0
	v_mov_b32_e32 v37, v0
	v_mov_b32_e32 v38, v0
	v_mov_b32_e32 v39, v0
	v_mov_b32_e32 v48, v0
	v_mov_b32_e32 v49, v0
	v_mov_b32_e32 v50, v0
	v_mov_b32_e32 v51, v0
	v_mov_b32_e32 v52, v0
	v_mov_b32_e32 v53, v0
	v_mov_b32_e32 v54, v0
	v_mov_b32_e32 v55, v0
	v_mov_b32_e32 v8, v0
	v_mov_b32_e32 v9, v0
	v_mov_b32_e32 v10, v0
	v_mov_b32_e32 v11, v0
	v_mov_b32_e32 v12, v0
	v_mov_b32_e32 v13, v0
	v_mov_b32_e32 v14, v0
	v_mov_b32_e32 v15, v0
	v_mov_b32_e32 v24, v0
	v_mov_b32_e32 v25, v0
	v_mov_b32_e32 v26, v0
	v_mov_b32_e32 v27, v0
	v_mov_b32_e32 v28, v0
	v_mov_b32_e32 v29, v0
	v_mov_b32_e32 v30, v0
	v_mov_b32_e32 v31, v0
	v_mov_b32_e32 v40, v0
	v_mov_b32_e32 v41, v0
	v_mov_b32_e32 v42, v0
	v_mov_b32_e32 v43, v0
	v_mov_b32_e32 v44, v0
	v_mov_b32_e32 v45, v0
	v_mov_b32_e32 v46, v0
	v_mov_b32_e32 v47, v0
	v_mov_b32_e32 v56, v0
	v_mov_b32_e32 v57, v0
	v_mov_b32_e32 v58, v0
	v_mov_b32_e32 v59, v0
	v_mov_b32_e32 v60, v0
	v_mov_b32_e32 v61, v0
	v_mov_b32_e32 v62, v0
	v_mov_b32_e32 v63, v0
	v_mov_b32_e32 v64, v0
	v_mov_b32_e32 v65, v0
	v_mov_b32_e32 v66, v0
	v_mov_b32_e32 v67, v0
	v_mov_b32_e32 v68, v0
	v_mov_b32_e32 v69, v0
	v_mov_b32_e32 v70, v0
	v_mov_b32_e32 v71, v0
	v_mov_b32_e32 v80, v0
	v_mov_b32_e32 v81, v0
	v_mov_b32_e32 v82, v0
	v_mov_b32_e32 v83, v0
	v_mov_b32_e32 v84, v0
	v_mov_b32_e32 v85, v0
	v_mov_b32_e32 v86, v0
	v_mov_b32_e32 v87, v0
	v_mov_b32_e32 v96, v0
	v_mov_b32_e32 v97, v0
	v_mov_b32_e32 v98, v0
	v_mov_b32_e32 v99, v0
	v_mov_b32_e32 v100, v0
	v_mov_b32_e32 v101, v0
	v_mov_b32_e32 v102, v0
	v_mov_b32_e32 v103, v0
	v_mov_b32_e32 v112, v0
	v_mov_b32_e32 v113, v0
	v_mov_b32_e32 v114, v0
	v_mov_b32_e32 v115, v0
	v_mov_b32_e32 v116, v0
	v_mov_b32_e32 v117, v0
	v_mov_b32_e32 v118, v0
	v_mov_b32_e32 v119, v0
	v_mov_b32_e32 v72, v0
	v_mov_b32_e32 v73, v0
	v_mov_b32_e32 v74, v0
	v_mov_b32_e32 v75, v0
	v_mov_b32_e32 v76, v0
	v_mov_b32_e32 v77, v0
	v_mov_b32_e32 v78, v0
	v_mov_b32_e32 v79, v0
	v_mov_b32_e32 v88, v0
	v_mov_b32_e32 v89, v0
	v_mov_b32_e32 v90, v0
	v_mov_b32_e32 v91, v0
	v_mov_b32_e32 v92, v0
	v_mov_b32_e32 v93, v0
	v_mov_b32_e32 v94, v0
	v_mov_b32_e32 v95, v0
	v_mov_b32_e32 v104, v0
	v_mov_b32_e32 v105, v0
	v_mov_b32_e32 v106, v0
	v_mov_b32_e32 v107, v0
	v_mov_b32_e32 v108, v0
	v_mov_b32_e32 v109, v0
	v_mov_b32_e32 v110, v0
	v_mov_b32_e32 v111, v0
	v_mov_b32_e32 v120, v0
	v_mov_b32_e32 v121, v0
	v_mov_b32_e32 v122, v0
	v_mov_b32_e32 v123, v0
	v_mov_b32_e32 v124, v0
	v_mov_b32_e32 v125, v0
	v_mov_b32_e32 v126, v0
	v_mov_b32_e32 v127, v0
	s_cmp_eq_u64 s[14:15], 0
	s_cbranch_scc1 .Lprio_750
	s_setprio 1

; template <class Epi, class Sched, bool ALIGN_EPI = false, bool SP2 = false>
; __device__ __forceinline__ void gemm_phase(PG8_LAS unsigned char* lds, const Gemm g, const Sched& S, const Epi& E) {
;     ...
;         const bool has_next = S.next(ui + 1, nxt);
;         const char* nA = has_next ? (const char*)g.A + (size_t)nxt.pm * tstep : cA; const char* nB = has_next ? (const char*)g.Bt + (size_t)nxt.pn * tstep : cB;
;     ...
; #pragma unroll
;         for (int a = 0; a < 2; ++a)
; #pragma unroll
;             for (int b = 0; b < 2; ++b)
; #pragma unroll
;                 for (int m = 0; m < 4; ++m)
; #pragma unroll
;                     for (int n = 0; n < 2; ++n) acc[a][b][m][n] = (f32x4){0.f, 0.f, 0.f, 0.f};
;         cur = nxt; cA = nA; cB = nB; ++ui;
.LBB0_834:
	s_ashr_i32 s73, s72, 31
	s_lshl_b64 s[6:7], s[72:73], 19
	s_add_u32 s74, s40, s6
	s_addc_u32 s75, s41, s7
	s_and_b64 s[6:7], s[0:1], exec
	s_cselect_b32 s5, s75, s79
	s_cselect_b32 s12, s74, s78
	s_ashr_i32 s71, s70, 31
	s_lshl_b64 s[6:7], s[70:71], 19
	s_add_u32 s76, s42, s6
	s_addc_u32 s77, s43, s7
	s_and_b64 s[6:7], s[0:1], exec
	s_cselect_b32 s56, s77, s9
	s_cselect_b32 s57, s76, s8
	s_add_u32 s6, s78, 0x40080
	.p2align 6
	s_addc_u32 s7, s79, 0
	s_add_u32 s71, s8, 0x100
	v_mov_b32_e32 v0, 0
	s_addc_u32 s73, s9, 0
	s_mov_b32 s80, -2
	v_mov_b32_e32 v1, v0
	v_mov_b32_e32 v2, v0
	v_mov_b32_e32 v3, v0
	v_mov_b32_e32 v4, v0
	v_mov_b32_e32 v5, v0
	v_mov_b32_e32 v6, v0
	v_mov_b32_e32 v7, v0
	v_mov_b32_e32 v16, v0
	v_mov_b32_e32 v17, v0
	v_mov_b32_e32 v18, v0
	v_mov_b32_e32 v19, v0
	v_mov_b32_e32 v20, v0
	v_mov_b32_e32 v21, v0
	v_mov_b32_e32 v22, v0
	v_mov_b32_e32 v23, v0
	v_mov_b32_e32 v32, v0
	v_mov_b32_e32 v33, v0
	v_mov_b32_e32 v34, v0
	v_mov_b32_e32 v35, v0
	v_mov_b32_e32 v36, v0
	v_mov_b32_e32 v37, v0
	v_mov_b32_e32 v38, v0
	v_mov_b32_e32 v39, v0
	v_mov_b32_e32 v48, v0
	v_mov_b32_e32 v49, v0
	v_mov_b32_e32 v50, v0
	v_mov_b32_e32 v51, v0
	v_mov_b32_e32 v52, v0
	v_mov_b32_e32 v53, v0
	v_mov_b32_e32 v54, v0
	v_mov_b32_e32 v55, v0
	v_mov_b32_e32 v8, v0
	v_mov_b32_e32 v9, v0
	v_mov_b32_e32 v10, v0
	v_mov_b32_e32 v11, v0
	v_mov_b32_e32 v12, v0
	v_mov_b32_e32 v13, v0
	v_mov_b32_e32 v14, v0
	v_mov_b32_e32 v15, v0
	v_mov_b32_e32 v24, v0
	v_mov_b32_e32 v25, v0
	v_mov_b32_e32 v26, v0
	v_mov_b32_e32 v27, v0
	v_mov_b32_e32 v28, v0
	v_mov_b32_e32 v29, v0
	v_mov_b32_e32 v30, v0
	v_mov_b32_e32 v31, v0
	v_mov_b32_e32 v40, v0
	v_mov_b32_e32 v41, v0
	v_mov_b32_e32 v42, v0
	v_mov_b32_e32 v43, v0
	v_mov_b32_e32 v44, v0
	v_mov_b32_e32 v45, v0
	v_mov_b32_e32 v46, v0
	v_mov_b32_e32 v47, v0
	v_mov_b32_e32 v56, v0
	v_mov_b32_e32 v57, v0
	v_mov_b32_e32 v58, v0
	v_mov_b32_e32 v59, v0
	v_mov_b32_e32 v60, v0
	v_mov_b32_e32 v61, v0
	v_mov_b32_e32 v62, v0
	v_mov_b32_e32 v63, v0
	v_mov_b32_e32 v64, v0
	v_mov_b32_e32 v65, v0
	v_mov_b32_e32 v66, v0
	v_mov_b32_e32 v67, v0
	v_mov_b32_e32 v68, v0
	v_mov_b32_e32 v69, v0
	v_mov_b32_e32 v70, v0
	v_mov_b32_e32 v71, v0
	v_mov_b32_e32 v80, v0
	v_mov_b32_e32 v81, v0
	v_mov_b32_e32 v82, v0
	v_mov_b32_e32 v83, v0
	v_mov_b32_e32 v84, v0
	v_mov_b32_e32 v85, v0
	v_mov_b32_e32 v86, v0
	v_mov_b32_e32 v87, v0
	v_mov_b32_e32 v96, v0
	v_mov_b32_e32 v97, v0
	v_mov_b32_e32 v98, v0
	v_mov_b32_e32 v99, v0
	v_mov_b32_e32 v104, v0
	v_mov_b32_e32 v105, v0
	v_mov_b32_e32 v106, v0
	v_mov_b32_e32 v107, v0
	v_mov_b32_e32 v112, v0
	v_mov_b32_e32 v113, v0
	v_mov_b32_e32 v114, v0
	v_mov_b32_e32 v115, v0
	v_mov_b32_e32 v116, v0
	v_mov_b32_e32 v117, v0
	v_mov_b32_e32 v118, v0
	v_mov_b32_e32 v119, v0
	v_mov_b32_e32 v72, v0
	v_mov_b32_e32 v73, v0
	v_mov_b32_e32 v74, v0
	v_mov_b32_e32 v75, v0
	v_mov_b32_e32 v76, v0
	v_mov_b32_e32 v77, v0
	v_mov_b32_e32 v78, v0
	v_mov_b32_e32 v79, v0
	v_mov_b32_e32 v88, v0
	v_mov_b32_e32 v89, v0
	v_mov_b32_e32 v90, v0
	v_mov_b32_e32 v91, v0
	v_mov_b32_e32 v92, v0
	v_mov_b32_e32 v93, v0
	v_mov_b32_e32 v94, v0
	v_mov_b32_e32 v95, v0
	v_mov_b32_e32 v100, v0
	v_mov_b32_e32 v101, v0
	v_mov_b32_e32 v102, v0
	v_mov_b32_e32 v103, v0
	v_mov_b32_e32 v108, v0
	v_mov_b32_e32 v109, v0
	v_mov_b32_e32 v110, v0
	v_mov_b32_e32 v111, v0
	v_mov_b32_e32 v120, v0
	v_mov_b32_e32 v121, v0
	v_mov_b32_e32 v122, v0
	v_mov_b32_e32 v123, v0
	v_mov_b32_e32 v124, v0
	v_mov_b32_e32 v125, v0
	v_mov_b32_e32 v126, v0
	v_mov_b32_e32 v127, v0
	s_cmp_eq_u64 s[20:21], 0
	s_cbranch_scc1 .Lprio_835
	s_setprio 1

; template <class Epi, class Sched, bool ALIGN_EPI = false, bool SP2 = false>
; __device__ __forceinline__ void gemm_phase(PG8_LAS unsigned char* lds, const Gemm g, const Sched& S, const Epi& E) {
;     ...
;         const bool has_next = S.next(ui + 1, nxt);
;         const char* nA = has_next ? (const char*)g.A + (size_t)nxt.pm * tstep : cA; const char* nB = has_next ? (const char*)g.Bt + (size_t)nxt.pn * tstep : cB;
;     ...
; #pragma unroll
;         for (int a = 0; a < 2; ++a)
; #pragma unroll
;             for (int b = 0; b < 2; ++b)
; #pragma unroll
;                 for (int m = 0; m < 4; ++m)
; #pragma unroll
;                     for (int n = 0; n < 2; ++n) acc[a][b][m][n] = (f32x4){0.f, 0.f, 0.f, 0.f};
;         cur = nxt; cA = nA; cB = nB; ++ui;
.LBB0_992:
	s_ashr_i32 s21, s20, 31
	s_lshl_b64 s[22:23], s[20:21], 19
	s_add_u32 s22, s26, s22
	s_addc_u32 s23, s27, s23
	s_and_b64 s[30:31], s[0:1], exec
	s_cselect_b32 s21, s23, s37
	s_cselect_b32 s51, s22, s36
	s_ashr_i32 s19, s18, 31
	s_lshl_b64 s[30:31], s[18:19], 19
	s_add_u32 s30, s28, s30
	s_addc_u32 s31, s29, s31
	s_and_b64 s[40:41], s[0:1], exec
	s_cselect_b32 s19, s31, s39
	s_cselect_b32 s52, s30, s38
	s_add_u32 s36, s36, 0x40080
	.p2align 6
	s_addc_u32 s37, s37, 0
	s_add_u32 s53, s38, 0x100
	v_mov_b32_e32 v0, 0
	s_addc_u32 s56, s39, 0
	s_mov_b32 s57, -2
	v_mov_b32_e32 v1, v0
	v_mov_b32_e32 v2, v0
	v_mov_b32_e32 v3, v0
	v_mov_b32_e32 v4, v0
	v_mov_b32_e32 v5, v0
	v_mov_b32_e32 v6, v0
	v_mov_b32_e32 v7, v0
	v_mov_b32_e32 v8, v0
	v_mov_b32_e32 v9, v0
	v_mov_b32_e32 v10, v0
	v_mov_b32_e32 v11, v0
	v_mov_b32_e32 v16, v0
	v_mov_b32_e32 v17, v0
	v_mov_b32_e32 v18, v0
	v_mov_b32_e32 v19, v0
	v_mov_b32_e32 v24, v0
	v_mov_b32_e32 v25, v0
	v_mov_b32_e32 v26, v0
	v_mov_b32_e32 v27, v0
	v_mov_b32_e32 v32, v0
	v_mov_b32_e32 v33, v0
	v_mov_b32_e32 v34, v0
	v_mov_b32_e32 v35, v0
	v_mov_b32_e32 v40, v0
	v_mov_b32_e32 v41, v0
	v_mov_b32_e32 v42, v0
	v_mov_b32_e32 v43, v0
	v_mov_b32_e32 v48, v0
	v_mov_b32_e32 v49, v0
	v_mov_b32_e32 v50, v0
	v_mov_b32_e32 v51, v0
	v_mov_b32_e32 v12, v0
	v_mov_b32_e32 v13, v0
	v_mov_b32_e32 v14, v0
	v_mov_b32_e32 v15, v0
	v_mov_b32_e32 v20, v0
	v_mov_b32_e32 v21, v0
	v_mov_b32_e32 v22, v0
	v_mov_b32_e32 v23, v0
	v_mov_b32_e32 v28, v0
	v_mov_b32_e32 v29, v0
	v_mov_b32_e32 v30, v0
	v_mov_b32_e32 v31, v0
	v_mov_b32_e32 v36, v0
	v_mov_b32_e32 v37, v0
	v_mov_b32_e32 v38, v0
	v_mov_b32_e32 v39, v0
	v_mov_b32_e32 v44, v0
	v_mov_b32_e32 v45, v0
	v_mov_b32_e32 v46, v0
	v_mov_b32_e32 v47, v0
	v_mov_b32_e32 v52, v0
	v_mov_b32_e32 v53, v0
	v_mov_b32_e32 v54, v0
	v_mov_b32_e32 v55, v0
	v_mov_b32_e32 v56, v0
	v_mov_b32_e32 v57, v0
	v_mov_b32_e32 v58, v0
	v_mov_b32_e32 v59, v0
	v_mov_b32_e32 v60, v0
	v_mov_b32_e32 v61, v0
	v_mov_b32_e32 v62, v0
	v_mov_b32_e32 v63, v0
	v_mov_b32_e32 v64, v0
	v_mov_b32_e32 v65, v0
	v_mov_b32_e32 v66, v0
	v_mov_b32_e32 v67, v0
	v_mov_b32_e32 v68, v0
	v_mov_b32_e32 v69, v0
	v_mov_b32_e32 v70, v0
	v_mov_b32_e32 v71, v0
	v_mov_b32_e32 v72, v0
	v_mov_b32_e32 v73, v0
	v_mov_b32_e32 v74, v0
	v_mov_b32_e32 v75, v0
	v_mov_b32_e32 v80, v0
	v_mov_b32_e32 v81, v0
	v_mov_b32_e32 v82, v0
	v_mov_b32_e32 v83, v0
	v_mov_b32_e32 v88, v0
	v_mov_b32_e32 v89, v0
	v_mov_b32_e32 v90, v0
	v_mov_b32_e32 v91, v0
	v_mov_b32_e32 v96, v0
	v_mov_b32_e32 v97, v0
	v_mov_b32_e32 v98, v0
	v_mov_b32_e32 v99, v0
	v_mov_b32_e32 v104, v0
	v_mov_b32_e32 v105, v0
	v_mov_b32_e32 v106, v0
	v_mov_b32_e32 v107, v0
	v_mov_b32_e32 v112, v0
	v_mov_b32_e32 v113, v0
	v_mov_b32_e32 v114, v0
	v_mov_b32_e32 v115, v0
	v_mov_b32_e32 v76, v0
	v_mov_b32_e32 v77, v0
	v_mov_b32_e32 v78, v0
	v_mov_b32_e32 v79, v0
	v_mov_b32_e32 v84, v0
	v_mov_b32_e32 v85, v0
	v_mov_b32_e32 v86, v0
	v_mov_b32_e32 v87, v0
	v_mov_b32_e32 v92, v0
	v_mov_b32_e32 v93, v0
	v_mov_b32_e32 v94, v0
	v_mov_b32_e32 v95, v0
	v_mov_b32_e32 v100, v0
	v_mov_b32_e32 v101, v0
	v_mov_b32_e32 v102, v0
	v_mov_b32_e32 v103, v0
	v_mov_b32_e32 v108, v0
	v_mov_b32_e32 v109, v0
	v_mov_b32_e32 v110, v0
	v_mov_b32_e32 v111, v0
	v_mov_b32_e32 v116, v0
	v_mov_b32_e32 v117, v0
	v_mov_b32_e32 v118, v0
	v_mov_b32_e32 v119, v0
	v_mov_b32_e32 v120, v0
	v_mov_b32_e32 v121, v0
	v_mov_b32_e32 v122, v0
	v_mov_b32_e32 v123, v0
	v_mov_b32_e32 v124, v0
	v_mov_b32_e32 v125, v0
	v_mov_b32_e32 v126, v0
	v_mov_b32_e32 v127, v0
	s_cmp_eq_u64 s[8:9], 0
	s_cbranch_scc1 .Lprio_993
	s_setprio 1
